# K1: K-loop load phase 4 issues its six LDS-DMA loads with an SGPR base pair + 32-bit lane offset (12 v_lshl_add_u64 fewer per iteration); bytes after the phase padded to the previous placement; on top
# speedup vs baseline: 1.0078x; 1.0044x over previous
; #define PG8_STAGE(bufoff, gbase, voff) do { _Pragma("unroll") for (int _i = 0; _i < 2; ++_i) { unsigned _vo = (voff)[_i]; asm volatile("" : "+v"(_vo));   \
;         __builtin_amdgcn_global_load_lds((const unsigned*)((const char*)(gbase) + _vo), (LAS unsigned*)(lds + (bufoff) + ldsw + _i * 8192), 16, 0, 0); } } while (0)
; #define PG8_LDA(dst, b, h) do { _Pragma("unroll") for (int m = 0; m < 4; ++m) _Pragma("unroll") for (int k = 0; k < 2; ++k) dst[m][k] = *(const LAS bf16x8*)(lds + PG8_SA(b, h) + aoff + m * 2048 + k * 1024); } while (0)
; #define PG8_LDB(dst, b, h) do { _Pragma("unroll") for (int n = 0; n < 2; ++n) _Pragma("unroll") for (int k = 0; k < 2; ++k) dst[n][k] = *(const LAS bf16x8*)(lds + PG8_SB(b, h) + boff + n * 2048 + k * 1024); } while (0)
; #define PG8_MMA(ai, bj, At, Bt) do { __builtin_amdgcn_s_setprio(1); _Pragma("unroll") for (int m = 0; m < 4; ++m) _Pragma("unroll") for (int n = 0; n < 2; ++n) _Pragma("unroll") for (int k = 0; k < 2; ++k) \
;         acc[ai][bj][m][n] = __builtin_amdgcn_mfma_f32_16x16x32_bf16(Bt[n][k], At[m][k], acc[ai][bj][m][n], 0, 0, 0); __builtin_amdgcn_s_setprio(0); } while (0)
; #define PG8_WAIT_V(n) asm volatile("s_waitcnt vmcnt(" #n ")" ::: "memory")
; #define PG8_WAIT_L(n) asm volatile("s_waitcnt lgkmcnt(" #n ")" ::: "memory")
; #define PG8_BAR __builtin_amdgcn_s_barrier()
; #define PG8_SCHED __builtin_amdgcn_sched_barrier(0)
; __device__ __forceinline__ void gemm_phase(LAS unsigned char* lds, const Call& C, const int tid, const Args& args) {
;     ...
;             PG8_LDB(B0, 1, 0); PG8_LDB(B1, 1, 1); PG8_SCHED; PG8_LDA(At, 1, 0); PG8_STAGE(PG8_SA(0, 1), a2 + hstepA, voffA);
;             PG8_WAIT_V(8); PG8_WAIT_L(0); PG8_BAR; PG8_MMA(0, 0, At, B0); PG8_MMA(0, 1, At, B1); PG8_BAR; PG8_SCHED;
;             PG8_LDA(At, 1, 1); PG8_STAGE(PG8_SB(1, 0), b3, voffB); PG8_STAGE(PG8_SB(1, 1), b3 + hstepB, voffB); PG8_STAGE(PG8_SA(1, 0), a3, voffA);
.Lp7_ph3:
	s_add_i32 s24, 0, 0x18000
	v_add_u32_e32 v80, s24, v245
	s_add_i32 s42, 0, 0x1c000
	ds_read_b128 v[136:139], v80
	ds_read_b128 v[140:143], v80 offset:1024
	ds_read_b128 v[144:147], v80 offset:2048
	ds_read_b128 v[148:151], v80 offset:3072
	v_add_u32_e32 v80, s42, v245
	ds_read_b128 v[152:155], v80
	ds_read_b128 v[156:159], v80 offset:1024
	ds_read_b128 v[160:163], v80 offset:2048
	ds_read_b128 v[164:167], v80 offset:3072
	s_add_u32 s34, s38, s22
	v_mov_b32_e32 v80, v205
	s_mov_b32 m0, s73
	ds_read_b128 v[168:171], v246 offset:32768
	ds_read_b128 v[172:175], v246 offset:33792
	ds_read_b128 v[176:179], v246 offset:34816
	ds_read_b128 v[180:183], v246 offset:35840
	ds_read_b128 v[184:187], v246 offset:36864
	ds_read_b128 v[188:191], v246 offset:37888
	ds_read_b128 v[192:195], v246 offset:38912
	ds_read_b128 v[196:199], v246 offset:39936
	s_addc_u32 s35, s39, 0
	s_nop 0
	global_load_lds_dwordx4 v80, s[34:35]
	v_mov_b32_e32 v80, v243
	s_mov_b32 m0, s4
	s_nop 0
	global_load_lds_dwordx4 v80, s[34:35]
	s_waitcnt vmcnt(8)
	s_waitcnt lgkmcnt(0)
	s_barrier
	s_setprio 1
	s_waitcnt lgkmcnt(0)
	v_mfma_f32_16x16x32_bf16 v[132:135], v[136:139], v[168:171], v[132:135]
	v_mfma_f32_16x16x32_bf16 v[128:131], v[144:147], v[168:171], v[128:131]
	v_mfma_f32_16x16x32_bf16 v[124:127], v[136:139], v[176:179], v[124:127]
	v_mfma_f32_16x16x32_bf16 v[120:123], v[144:147], v[176:179], v[120:123]
	v_mfma_f32_16x16x32_bf16 v[108:111], v[136:139], v[184:187], v[108:111]
	v_mfma_f32_16x16x32_bf16 v[104:107], v[144:147], v[184:187], v[104:107]
	v_mfma_f32_16x16x32_bf16 v[90:93], v[136:139], v[192:195], v[92:95]
	v_mfma_f32_16x16x32_bf16 v[86:89], v[144:147], v[192:195], v[86:89]
	v_mfma_f32_16x16x32_bf16 v[132:135], v[140:143], v[172:175], v[132:135]
	v_mfma_f32_16x16x32_bf16 v[128:131], v[148:151], v[172:175], v[128:131]
	v_mfma_f32_16x16x32_bf16 v[124:127], v[140:143], v[180:183], v[124:127]
	v_mfma_f32_16x16x32_bf16 v[120:123], v[148:151], v[180:183], v[120:123]
	v_mfma_f32_16x16x32_bf16 v[108:111], v[140:143], v[188:191], v[108:111]
	v_mfma_f32_16x16x32_bf16 v[104:107], v[148:151], v[188:191], v[104:107]
	v_mfma_f32_16x16x32_bf16 v[92:95], v[140:143], v[196:199], v[90:93]
	v_mfma_f32_16x16x32_bf16 v[88:91], v[148:151], v[196:199], v[86:89]
	s_setprio 0
	s_setprio 1
	v_mfma_f32_16x16x32_bf16 v[116:119], v[152:155], v[168:171], v[116:119]
	v_mfma_f32_16x16x32_bf16 v[112:115], v[160:163], v[168:171], v[112:115]
	v_mfma_f32_16x16x32_bf16 v[100:103], v[152:155], v[176:179], v[100:103]
	v_mfma_f32_16x16x32_bf16 v[96:99], v[160:163], v[176:179], v[96:99]
	v_mfma_f32_16x16x32_bf16 v[76:79], v[152:155], v[184:187], v[76:79]
	v_mfma_f32_16x16x32_bf16 v[72:75], v[160:163], v[184:187], v[72:75]
	v_mfma_f32_16x16x32_bf16 v[68:71], v[152:155], v[192:195], v[68:71]
	v_mfma_f32_16x16x32_bf16 v[60:63], v[160:163], v[192:195], v[60:63]
	v_mfma_f32_16x16x32_bf16 v[116:119], v[156:159], v[172:175], v[116:119]
	v_mfma_f32_16x16x32_bf16 v[112:115], v[164:167], v[172:175], v[112:115]
	v_mfma_f32_16x16x32_bf16 v[100:103], v[156:159], v[180:183], v[100:103]
	v_mfma_f32_16x16x32_bf16 v[96:99], v[164:167], v[180:183], v[96:99]
	v_mfma_f32_16x16x32_bf16 v[76:79], v[156:159], v[188:191], v[76:79]
	v_mfma_f32_16x16x32_bf16 v[72:75], v[164:167], v[188:191], v[72:75]
	v_mfma_f32_16x16x32_bf16 v[68:71], v[156:159], v[196:199], v[68:71]
	v_mfma_f32_16x16x32_bf16 v[60:63], v[164:167], v[196:199], v[60:63]
	s_setprio 0
	s_barrier
	v_mov_b32_e32 v80, v242
	ds_read_b128 v[168:171], v246 offset:49152
	ds_read_b128 v[172:175], v246 offset:50176
	ds_read_b128 v[176:179], v246 offset:51200
	ds_read_b128 v[180:183], v246 offset:52224
	ds_read_b128 v[184:187], v246 offset:53248
	ds_read_b128 v[188:191], v246 offset:54272
	ds_read_b128 v[192:195], v246 offset:55296
	ds_read_b128 v[196:199], v246 offset:56320
	s_add_i32 s24, s24, s23
	s_add_u32 vcc_lo, s40, s18
	s_addc_u32 vcc_hi, s41, s19
	s_mov_b32 m0, s24
	s_nop 0
	global_load_lds_dwordx4 v80, vcc
	v_mov_b32_e32 v80, v244
	s_add_i32 m0, s24, 0x2000
	s_nop 0
	global_load_lds_dwordx4 v80, vcc
	s_add_i32 s24, s42, s23
	s_add_u32 vcc_lo, s0, s18
	s_addc_u32 vcc_hi, s1, s19
	v_mov_b32_e32 v80, v242
	s_mov_b32 m0, s24
	s_nop 0
	global_load_lds_dwordx4 v80, vcc
	v_mov_b32_e32 v80, v244
	s_add_i32 m0, s24, 0x2000
	s_nop 0
	global_load_lds_dwordx4 v80, vcc
	s_add_u32 vcc_lo, s38, s18
	s_addc_u32 vcc_hi, s39, s19
	v_mov_b32_e32 v80, v205
	s_mov_b32 m0, s14
	s_nop 0
	global_load_lds_dwordx4 v80, vcc
	v_mov_b32_e32 v80, v243
	s_mov_b32 m0, s52
	s_nop 0
	global_load_lds_dwordx4 v80, vcc
	s_branch .Lk1_over
	s_nop 0
	s_nop 0
	s_nop 0
	s_nop 0
	s_nop 0
	s_nop 0
	s_nop 0
	s_nop 0
	s_nop 0
	s_nop 0
	s_nop 0
; #define PG8_MMA(ai, bj, At, Bt) do { __builtin_amdgcn_s_setprio(1); _Pragma("unroll") for (int m = 0; m < 4; ++m) _Pragma("unroll") for (int n = 0; n < 2; ++n) _Pragma("unroll") for (int k = 0; k < 2; ++k) \
;         acc[ai][bj][m][n] = __builtin_amdgcn_mfma_f32_16x16x32_bf16(Bt[n][k], At[m][k], acc[ai][bj][m][n], 0, 0, 0); __builtin_amdgcn_s_setprio(0); } while (0)
; #define PG8_WAIT_V(n) asm volatile("s_waitcnt vmcnt(" #n ")" ::: "memory")
; #define PG8_WAIT_L(n) asm volatile("s_waitcnt lgkmcnt(" #n ")" ::: "memory")
; #define PG8_BAR __builtin_amdgcn_s_barrier()
; #define PG8_SCHED __builtin_amdgcn_sched_barrier(0)
; __device__ __forceinline__ void gemm_phase(LAS unsigned char* lds, const Call& C, const int tid, const Args& args) {
;     ...
;             PG8_WAIT_V(8); PG8_WAIT_L(0); PG8_BAR; PG8_MMA(1, 0, At, B0); PG8_MMA(1, 1, At, B1); PG8_BAR; PG8_SCHED;
;         }
.Lk1_over:
	s_waitcnt vmcnt(8)
	s_waitcnt lgkmcnt(0)
	s_barrier
	s_setprio 1
	s_waitcnt lgkmcnt(0)
	v_mfma_f32_16x16x32_bf16 v[64:67], v[136:139], v[168:171], v[64:67]
	v_mfma_f32_16x16x32_bf16 v[56:59], v[144:147], v[168:171], v[56:59]
	v_mfma_f32_16x16x32_bf16 v[52:55], v[136:139], v[176:179], v[52:55]
	v_mfma_f32_16x16x32_bf16 v[48:51], v[144:147], v[176:179], v[48:51]
	v_mfma_f32_16x16x32_bf16 v[36:39], v[136:139], v[184:187], v[36:39]
	v_mfma_f32_16x16x32_bf16 v[32:35], v[144:147], v[184:187], v[32:35]
	v_mfma_f32_16x16x32_bf16 v[20:23], v[136:139], v[192:195], v[20:23]
	v_mfma_f32_16x16x32_bf16 v[16:19], v[144:147], v[192:195], v[16:19]
	v_mfma_f32_16x16x32_bf16 v[64:67], v[140:143], v[172:175], v[64:67]
	v_mfma_f32_16x16x32_bf16 v[56:59], v[148:151], v[172:175], v[56:59]
	v_mfma_f32_16x16x32_bf16 v[52:55], v[140:143], v[180:183], v[52:55]
	v_mfma_f32_16x16x32_bf16 v[48:51], v[148:151], v[180:183], v[48:51]
	v_mfma_f32_16x16x32_bf16 v[36:39], v[140:143], v[188:191], v[36:39]
	v_mfma_f32_16x16x32_bf16 v[32:35], v[148:151], v[188:191], v[32:35]
	v_mfma_f32_16x16x32_bf16 v[20:23], v[140:143], v[196:199], v[20:23]
	v_mfma_f32_16x16x32_bf16 v[16:19], v[148:151], v[196:199], v[16:19]
	s_setprio 0
	s_setprio 1
	v_mfma_f32_16x16x32_bf16 v[44:47], v[152:155], v[168:171], v[44:47]
	v_mfma_f32_16x16x32_bf16 v[40:43], v[160:163], v[168:171], v[40:43]
	v_mfma_f32_16x16x32_bf16 v[28:31], v[152:155], v[176:179], v[28:31]
	v_mfma_f32_16x16x32_bf16 v[24:27], v[160:163], v[176:179], v[24:27]
	v_mfma_f32_16x16x32_bf16 v[12:15], v[152:155], v[184:187], v[12:15]
	v_mfma_f32_16x16x32_bf16 v[8:11], v[160:163], v[184:187], v[8:11]
	v_mfma_f32_16x16x32_bf16 v[4:7], v[152:155], v[192:195], v[4:7]
	v_mfma_f32_16x16x32_bf16 v[0:3], v[160:163], v[192:195], v[0:3]
	v_mfma_f32_16x16x32_bf16 v[44:47], v[156:159], v[172:175], v[44:47]
	v_mfma_f32_16x16x32_bf16 v[40:43], v[164:167], v[172:175], v[40:43]
	v_mfma_f32_16x16x32_bf16 v[28:31], v[156:159], v[180:183], v[28:31]
	v_mfma_f32_16x16x32_bf16 v[24:27], v[164:167], v[180:183], v[24:27]
	v_mfma_f32_16x16x32_bf16 v[12:15], v[156:159], v[188:191], v[12:15]
	v_mfma_f32_16x16x32_bf16 v[8:11], v[164:167], v[188:191], v[8:11]
	v_mfma_f32_16x16x32_bf16 v[4:7], v[156:159], v[196:199], v[4:7]
	v_mfma_f32_16x16x32_bf16 v[0:3], v[164:167], v[196:199], v[0:3]
	s_setprio 0
	s_barrier
	s_add_u32 s16, s16, 0x100
	s_addc_u32 s17, s17, 0
	s_cmp_ge_u32 s25, s12
	s_mov_b64 s[0:1], s[8:9]
	s_mov_b32 s24, s25
	s_cbranch_scc0 .LBB0_282
	s_and_b64 vcc, exec, s[80:81]
	s_cbranch_vccz .LBB0_285
